# attention main loop: waves 4-7 run a copy with tile-step sections reordered (QK after finishSM/PV) so SIMD partners interleave MFMA and softmax VALU
# speedup vs baseline: 1.0285x; 1.0163x over previous
.LBB0_467:
	s_nop 8
	v_max_f32_e32 v33, v17, v17
	v_max_f32_e32 v34, v16, v16
	v_max_f32_e32 v33, v34, v33
	v_max3_f32 v33, v33, v18, v19
	v_max3_f32 v33, v33, v20, v21
	v_max3_f32 v33, v33, v22, v23
	v_max3_f32 v33, v33, v24, v25
	v_max3_f32 v33, v33, v26, v27
	v_max3_f32 v33, v33, v28, v29
	v_max3_f32 v33, v33, v30, v31
	v_max3_f32 v33, v33, v0, v1
	v_max3_f32 v33, v33, v2, v3
	v_max3_f32 v33, v33, v4, v5
	v_max3_f32 v33, v33, v6, v7
	v_max3_f32 v33, v33, v8, v9
	v_max3_f32 v33, v33, v10, v11
	v_max3_f32 v33, v33, v12, v13
	v_max3_f32 v33, v33, v14, v15
	v_mov_b32_e32 v34, v33
	s_nop 1
	v_permlane32_swap_b32_e32 v33, v34
	v_max_f32_e32 v34, v34, v34
	v_max_f32_e32 v33, v33, v33
	v_max_f32_e32 v33, v33, v34
	s_add_i32 s4, 0, 0x10000
	v_add_f32_e32 v34, 0x7149f2ca, v33
	s_cmp_lg_u32 0, -1
	v_cmp_ge_f32_e32 vcc, s16, v34
	s_cselect_b32 s25, 0, 0
	s_cmp_eq_u64 vcc, exec
	s_cselect_b64 vcc, -1, 0
	s_and_b64 s[30:31], s[64:65], exec
	s_cselect_b32 s5, s24, 64
	v_add_u32_e32 v34, s5, v158
	v_ashrrev_i32_e32 v35, 31, v34
	v_lshlrev_b64 v[42:43], 10, v[34:35]
	v_add_u32_e32 v34, 32, v34
	v_lshlrev_b32_e32 v32, 3, v32
	v_ashrrev_i32_e32 v35, 31, v34
	v_lshlrev_b32_e32 v32, 1, v32
	v_lshlrev_b64 v[46:47], 10, v[34:35]
	v_or_b32_e32 v42, v42, v32
	v_or_b32_e32 v46, v46, v32
	v_lshl_add_u64 v[36:37], s[68:69], 0, v[42:43]
	v_lshl_add_u64 v[38:39], s[68:69], 0, v[46:47]
	v_lshl_add_u64 v[42:43], s[6:7], 0, v[42:43]
	v_lshl_add_u64 v[46:47], s[6:7], 0, v[46:47]
	global_load_dwordx4 v[34:37], v[36:37], off
	s_nop 0
	global_load_dwordx4 v[38:41], v[38:39], off
	v_and_b32_e32 v161, 63, v148
	global_load_dwordx4 v[42:45], v[42:43], off
	v_and_b32_e32 v50, 0x3fffffc0, v148
	global_load_dwordx4 v[46:49], v[46:47], off
	v_lshlrev_b32_e32 v51, 4, v161
	v_lshl_add_u32 v152, v50, 2, s4
	v_lshlrev_b32_e32 v50, 3, v161
	v_lshlrev_b32_e32 v52, 1, v161
	v_and_b32_e32 v51, 0xc0, v51
	v_max_f32_e32 v33, 0xf149f2ca, v33
	v_and_b32_e32 v52, 32, v52
	v_and_b32_e32 v53, 0x100, v50
	v_and_or_b32 v50, v50, 24, v51
	v_or3_b32 v154, v50, v52, v53
	v_sub_f32_e32 v50, 0xf149f2ca, v33
	v_cndmask_b32_e32 v177, v33, v146, vcc
	v_exp_f32_e32 v50, v50
	v_sub_f32_e32 v16, v16, v177
	v_sub_f32_e32 v17, v17, v177
	v_sub_f32_e32 v18, v18, v177
	v_sub_f32_e32 v19, v19, v177
	v_sub_f32_e32 v20, v20, v177
	v_sub_f32_e32 v21, v21, v177
	v_sub_f32_e32 v22, v22, v177
	v_sub_f32_e32 v23, v23, v177
	v_sub_f32_e32 v24, v24, v177
	v_sub_f32_e32 v25, v25, v177
	v_sub_f32_e32 v26, v26, v177
	v_sub_f32_e32 v27, v27, v177
	v_sub_f32_e32 v28, v28, v177
	v_sub_f32_e32 v29, v29, v177
	v_sub_f32_e32 v30, v30, v177
	v_sub_f32_e32 v31, v31, v177
	v_exp_f32_e32 v196, v16
	v_exp_f32_e32 v198, v17
	v_exp_f32_e32 v194, v18
	v_exp_f32_e32 v197, v19
	v_exp_f32_e32 v192, v20
	v_exp_f32_e32 v195, v21
	v_exp_f32_e32 v191, v22
	v_exp_f32_e32 v193, v23
	v_exp_f32_e32 v188, v24
	v_exp_f32_e32 v190, v25
	v_exp_f32_e32 v186, v26
	v_exp_f32_e32 v189, v27
	v_exp_f32_e32 v184, v28
	v_exp_f32_e32 v187, v29
	v_exp_f32_e32 v183, v30
	v_exp_f32_e32 v185, v31
	s_waitcnt vmcnt(0)
	s_cmp_lg_u32 s14, 0
	v_mov_b32_e32 v136, v130
	v_mov_b32_e32 v137, v130
	v_mov_b32_e32 v134, v130
	v_mov_b32_e32 v135, v130
	v_sub_f32_e32 v65, v15, v177
	v_sub_f32_e32 v64, v14, v177
	v_sub_f32_e32 v67, v13, v177
	v_sub_f32_e32 v66, v12, v177
	v_sub_f32_e32 v69, v11, v177
	v_sub_f32_e32 v68, v10, v177
	v_sub_f32_e32 v71, v9, v177
	v_sub_f32_e32 v70, v8, v177
	v_sub_f32_e32 v73, v7, v177
	v_sub_f32_e32 v72, v6, v177
	v_sub_f32_e32 v75, v5, v177
	v_sub_f32_e32 v74, v4, v177
	v_sub_f32_e32 v77, v3, v177
	v_sub_f32_e32 v76, v2, v177
	v_sub_f32_e32 v79, v1, v177
	v_sub_f32_e32 v78, v0, v177
	v_cndmask_b32_e64 v156, v50, 1.0, vcc
	s_cselect_b64 s[66:67], -1, 0
	s_cmp_eq_u32 s14, 0
	v_cmp_gt_u32_e64 s[4:5], 32, v161
	v_add_u32_e32 v176, s25, v154
	v_lshl_add_u32 v173, v155, 2, v152
	s_waitcnt vmcnt(3)
	ds_write_b128 v174, v[34:37] offset:16384
	s_waitcnt vmcnt(2)
	ds_write_b128 v175, v[38:41] offset:16384
	s_waitcnt vmcnt(1)
	ds_write_b128 v171, v[42:45] offset:49152
	s_waitcnt vmcnt(0)
	ds_write_b128 v172, v[46:49] offset:49152
	s_waitcnt lgkmcnt(0)
	s_barrier
	s_cbranch_scc1 .LBB0_484
	v_mov_b32_e32 v33, v128
	s_cmp_lg_u32 0, -1
	v_lshl_add_u64 v[138:139], s[6:7], 0, v[32:33]
	s_cselect_b32 s6, 0, 0
	s_addk_i32 s6, 0x4000
	v_mov_b32_e32 v157, 0
	v_lshl_add_u64 v[132:133], s[68:69], 0, v[32:33]
	v_sub_u32_e32 v178, v155, v159
	v_lshl_add_u32 v179, v151, 2, v152
	v_add_u32_e32 v180, s6, v154
	s_add_i32 s29, s27, -4
	s_mov_b32 s30, 3
	v_mov_b32_e32 v48, 0
	v_mov_b32_e32 v49, v157
	v_mov_b32_e32 v50, v157
	v_mov_b32_e32 v51, v157
	v_mov_b32_e32 v52, v157
	v_mov_b32_e32 v53, v157
	v_mov_b32_e32 v54, v157
	v_mov_b32_e32 v55, v157
	v_mov_b32_e32 v56, v157
	v_mov_b32_e32 v57, v157
	v_mov_b32_e32 v58, v157
	v_mov_b32_e32 v59, v157
	v_mov_b32_e32 v60, v157
	v_mov_b32_e32 v61, v157
	v_mov_b32_e32 v62, v157
	v_mov_b32_e32 v63, v157
	v_mov_b32_e32 v32, 0
	v_mov_b32_e32 v33, v157
	v_mov_b32_e32 v34, v157
	v_mov_b32_e32 v35, v157
	v_mov_b32_e32 v36, v157
	v_mov_b32_e32 v37, v157
	v_mov_b32_e32 v38, v157
	v_mov_b32_e32 v39, v157
	v_mov_b32_e32 v40, v157
	v_mov_b32_e32 v41, v157
	v_mov_b32_e32 v42, v157
	v_mov_b32_e32 v43, v157
	v_mov_b32_e32 v44, v157
	v_mov_b32_e32 v45, v157
	v_mov_b32_e32 v46, v157
	v_mov_b32_e32 v47, v157
	v_mov_b32_e32 v16, 0
	v_mov_b32_e32 v17, v157
	v_mov_b32_e32 v18, v157
	v_mov_b32_e32 v19, v157
	v_mov_b32_e32 v20, v157
	v_mov_b32_e32 v21, v157
	v_mov_b32_e32 v22, v157
	v_mov_b32_e32 v23, v157
	v_mov_b32_e32 v24, v157
	v_mov_b32_e32 v25, v157
	v_mov_b32_e32 v26, v157
	v_mov_b32_e32 v27, v157
	v_mov_b32_e32 v28, v157
	v_mov_b32_e32 v29, v157
	v_mov_b32_e32 v30, v157
	v_mov_b32_e32 v31, v157
	v_mov_b32_e32 v0, 0
	v_mov_b32_e32 v1, v157
	v_mov_b32_e32 v2, v157
	v_mov_b32_e32 v3, v157
	v_mov_b32_e32 v4, v157
	v_mov_b32_e32 v5, v157
	v_mov_b32_e32 v6, v157
	v_mov_b32_e32 v7, v157
	v_mov_b32_e32 v8, v157
	v_mov_b32_e32 v9, v157
	v_mov_b32_e32 v10, v157
	v_mov_b32_e32 v11, v157
	v_mov_b32_e32 v12, v157
	v_mov_b32_e32 v13, v157
	v_mov_b32_e32 v14, v157
	v_mov_b32_e32 v15, v157
	s_cmp_ge_u32 s93, 4
	s_cbranch_scc1 .LvB_469

.LvB_469:
	v_add_f32_e32 v131, 0, v196
	v_add_f32_e32 v131, v198, v131
	v_add_f32_e32 v131, v194, v131
	v_add_f32_e32 v131, v197, v131
	v_add_f32_e32 v131, v192, v131
	v_add_f32_e32 v131, v195, v131
	v_add_f32_e32 v131, v191, v131
	v_add_f32_e32 v131, v193, v131
	v_add_f32_e32 v131, v188, v131
	v_add_f32_e32 v131, v190, v131
	v_add_f32_e32 v131, v186, v131
	v_add_f32_e32 v131, v189, v131
	v_exp_f32_e32 v78, v78
	v_add_f32_e32 v131, v184, v131
	v_exp_f32_e32 v79, v79
	v_add_f32_e32 v131, v187, v131
	v_exp_f32_e32 v76, v76
	v_add_f32_e32 v131, v183, v131
	v_exp_f32_e32 v77, v77
	v_add_f32_e32 v131, v185, v131
	v_exp_f32_e32 v74, v74
	v_add_f32_e32 v131, v78, v131
	v_exp_f32_e32 v75, v75
	v_add_f32_e32 v131, v79, v131
	v_exp_f32_e32 v72, v72
	v_add_f32_e32 v131, v76, v131
	v_exp_f32_e32 v73, v73
	v_add_f32_e32 v131, v77, v131
	v_exp_f32_e32 v70, v70
	v_add_f32_e32 v131, v74, v131
	v_exp_f32_e32 v71, v71
	v_add_f32_e32 v131, v75, v131
	v_exp_f32_e32 v68, v68
	v_add_f32_e32 v131, v72, v131
	v_exp_f32_e32 v69, v69
	v_add_f32_e32 v131, v73, v131
	v_exp_f32_e32 v66, v66
	v_add_f32_e32 v131, v70, v131
	v_exp_f32_e32 v67, v67
	v_add_f32_e32 v131, v71, v131
	v_exp_f32_e32 v64, v64
	v_add_f32_e32 v131, v68, v131
	v_exp_f32_e32 v65, v65
	v_add_f32_e32 v131, v69, v131
	v_add_f32_e32 v131, v66, v131
	v_add_f32_e32 v131, v67, v131
	v_add_f32_e32 v131, v64, v131
	v_add_f32_e32 v181, v65, v131
	v_mov_b32_e32 v182, v181
	v_cvt_pk_bf16_f32 v196, v196, v198
	v_cvt_pk_bf16_f32 v197, v194, v197
	v_cvt_pk_bf16_f32 v198, v192, v195
	v_cvt_pk_bf16_f32 v199, v191, v193
	s_add_i32 s24, s30, -1
	s_nop 0
	v_permlane32_swap_b32_e32 v181, v182
	v_permlane32_swap_b32_e32 v197, v199
	v_cvt_pk_bf16_f32 v188, v188, v190
	v_cvt_pk_bf16_f32 v189, v186, v189
	v_cvt_pk_bf16_f32 v190, v184, v187
	v_cvt_pk_bf16_f32 v191, v183, v185
	v_cvt_pk_bf16_f32 v184, v78, v79
	v_cvt_pk_bf16_f32 v185, v76, v77
	v_cvt_pk_bf16_f32 v186, v74, v75
	v_cvt_pk_bf16_f32 v187, v72, v73
	v_cvt_pk_bf16_f32 v192, v70, v71
	v_cvt_pk_bf16_f32 v193, v68, v69
	v_cvt_pk_bf16_f32 v194, v66, v67
	v_cvt_pk_bf16_f32 v195, v64, v65
	v_permlane32_swap_b32_e32 v196, v198
	v_permlane32_swap_b32_e32 v188, v190
	v_permlane32_swap_b32_e32 v189, v191
	v_permlane32_swap_b32_e32 v184, v186
	v_permlane32_swap_b32_e32 v185, v187
	v_permlane32_swap_b32_e32 v192, v194
	v_permlane32_swap_b32_e32 v193, v195
	s_add_i32 s25, s29, 1
	s_and_b64 s[6:7], s[64:65], exec
	s_cselect_b32 s25, s25, s24
	s_lshl_b32 s24, s25, 6
	v_add_u32_e32 v64, s24, v158
	v_add_u32_e32 v66, s24, v170
	v_ashrrev_i32_e32 v65, 31, v64
	v_ashrrev_i32_e32 v67, 31, v66
	v_lshlrev_b64 v[72:73], 10, v[64:65]
	v_lshlrev_b64 v[74:75], 10, v[66:67]
	v_lshl_add_u64 v[64:65], v[132:133], 0, v[72:73]
	v_lshl_add_u64 v[68:69], v[132:133], 0, v[74:75]
	v_lshl_add_u64 v[72:73], v[138:139], 0, v[72:73]
	v_lshl_add_u64 v[76:77], v[138:139], 0, v[74:75]
	global_load_dwordx4 v[64:67], v[64:65], off
	s_nop 0
	global_load_dwordx4 v[68:71], v[68:69], off
	s_nop 0
	global_load_dwordx4 v[72:75], v[72:73], off
	s_nop 0
	global_load_dwordx4 v[76:79], v[76:77], off
	ds_read_b64_tr_b16 v[200:201], v176 offset:0
	ds_read_b64_tr_b16 v[202:203], v176 offset:0x800
	ds_read_b64_tr_b16 v[204:205], v176 offset:0x1000
	ds_read_b64_tr_b16 v[206:207], v176 offset:0x1800
	ds_read_b64_tr_b16 v[208:209], v176 offset:0x2000
	ds_read_b64_tr_b16 v[210:211], v176 offset:0x2800
	ds_read_b64_tr_b16 v[212:213], v176 offset:0x3000
	ds_read_b64_tr_b16 v[214:215], v176 offset:0x3800
	s_waitcnt lgkmcnt(0)
	s_nop 0
	v_mfma_f32_32x32x16_bf16 v[48:63], v[196:199], v[200:203], v[48:63]
	ds_read_b64_tr_b16 v[200:201], v176 offset:0x200
	ds_read_b64_tr_b16 v[202:203], v176 offset:0xa00
	v_mfma_f32_32x32x16_bf16 v[48:63], v[188:191], v[204:207], v[48:63]
	ds_read_b64_tr_b16 v[204:205], v176 offset:0x1200
	ds_read_b64_tr_b16 v[206:207], v176 offset:0x1a00
	v_mfma_f32_32x32x16_bf16 v[48:63], v[184:187], v[208:211], v[48:63]
	ds_read_b64_tr_b16 v[208:209], v176 offset:0x2200
	ds_read_b64_tr_b16 v[210:211], v176 offset:0x2a00
	ds_read_b64_tr_b16 v[216:217], v176 offset:0x3200
	ds_read_b64_tr_b16 v[218:219], v176 offset:0x3a00
	s_waitcnt lgkmcnt(0)
	v_mfma_f32_32x32x16_bf16 v[48:63], v[192:195], v[212:215], v[48:63]
	v_mfma_f32_32x32x16_bf16 v[32:47], v[196:199], v[200:203], v[32:47]
	ds_read_b64_tr_b16 v[200:201], v176 offset:0x400
	ds_read_b64_tr_b16 v[202:203], v176 offset:0xc00
	v_mfma_f32_32x32x16_bf16 v[32:47], v[188:191], v[204:207], v[32:47]
	ds_read_b64_tr_b16 v[204:205], v176 offset:0x1400
	ds_read_b64_tr_b16 v[206:207], v176 offset:0x1c00
	v_mfma_f32_32x32x16_bf16 v[32:47], v[184:187], v[208:211], v[32:47]
	ds_read_b64_tr_b16 v[208:209], v176 offset:0x2400
	ds_read_b64_tr_b16 v[210:211], v176 offset:0x2c00
	ds_read_b64_tr_b16 v[212:213], v176 offset:0x3400
	ds_read_b64_tr_b16 v[214:215], v176 offset:0x3c00
	s_waitcnt lgkmcnt(0)
	v_mfma_f32_32x32x16_bf16 v[32:47], v[192:195], v[216:219], v[32:47]
	v_mfma_f32_32x32x16_bf16 v[16:31], v[196:199], v[200:203], v[16:31]
	ds_read_b64_tr_b16 v[200:201], v176 offset:0x600
	ds_read_b64_tr_b16 v[202:203], v176 offset:0xe00
	v_mfma_f32_32x32x16_bf16 v[16:31], v[188:191], v[204:207], v[16:31]
	ds_read_b64_tr_b16 v[204:205], v176 offset:0x1600
	ds_read_b64_tr_b16 v[206:207], v176 offset:0x1e00
	v_mfma_f32_32x32x16_bf16 v[16:31], v[184:187], v[208:211], v[16:31]
	ds_read_b64_tr_b16 v[208:209], v176 offset:0x2600
	ds_read_b64_tr_b16 v[210:211], v176 offset:0x2e00
	ds_read_b64_tr_b16 v[216:217], v176 offset:0x3600
	ds_read_b64_tr_b16 v[218:219], v176 offset:0x3e00
	s_waitcnt lgkmcnt(0)
	v_mfma_f32_32x32x16_bf16 v[16:31], v[192:195], v[212:215], v[16:31]
	v_mfma_f32_32x32x16_bf16 v[0:15], v[196:199], v[200:203], v[0:15]
	v_mfma_f32_32x32x16_bf16 v[0:15], v[188:191], v[204:207], v[0:15]
	v_mfma_f32_32x32x16_bf16 v[0:15], v[184:187], v[208:211], v[0:15]
	v_mfma_f32_32x32x16_bf16 v[0:15], v[192:195], v[216:219], v[0:15]
	s_add_i32 s80, s30, -2
	s_add_i32 s81, s29, 2
	s_and_b64 s[6:7], s[64:65], exec
	s_cselect_b32 s7, s81, s80
	s_lshl_b32 s6, s7, 6
	v_add_u32_e32 v80, s6, v178
	v_cvt_f32_i32_e32 v80, v80
	ds_read_b128 v[230:233], v167 offset:49152
	ds_read_b128 v[234:237], v162 offset:49152
	v_mov_b32_e32 v226, v130
	v_mov_b32_e32 v227, v130
	s_cmp_lt_i32 s7, s28
	v_mul_f32_e32 v80, v130, v80
	v_pk_add_f32 v[96:97], v[128:129], v[80:81] op_sel_hi:[1,0]
	v_pk_fma_f32 v[98:99], v[136:137], s[10:11], v[80:81] op_sel_hi:[1,1,0]
	v_pk_fma_f32 v[100:101], v[136:137], s[16:17], v[80:81] op_sel_hi:[1,1,0]
	v_pk_fma_f32 v[102:103], v[136:137], s[18:19], v[80:81] op_sel_hi:[1,1,0]
	v_pk_fma_f32 v[104:105], v[136:137], s[22:23], v[80:81] op_sel_hi:[1,1,0]
	v_pk_fma_f32 v[106:107], v[136:137], s[40:41], v[80:81] op_sel_hi:[1,1,0]
	v_pk_fma_f32 v[108:109], v[136:137], s[42:43], v[80:81] op_sel_hi:[1,1,0]
	v_pk_fma_f32 v[110:111], v[136:137], s[44:45], v[80:81] op_sel_hi:[1,1,0]
	v_pk_fma_f32 v[94:95], v[226:227], s[46:47], v[80:81] op_sel_hi:[1,1,0]
	v_pk_fma_f32 v[92:93], v[226:227], s[48:49], v[80:81] op_sel_hi:[1,1,0]
	v_pk_fma_f32 v[90:91], v[226:227], s[50:51], v[80:81] op_sel_hi:[1,1,0]
	v_pk_fma_f32 v[88:89], v[226:227], s[52:53], v[80:81] op_sel_hi:[1,1,0]
	v_pk_fma_f32 v[86:87], v[226:227], s[54:55], v[80:81] op_sel_hi:[1,1,0]
	v_pk_fma_f32 v[84:85], v[226:227], s[56:57], v[80:81] op_sel_hi:[1,1,0]
	v_pk_fma_f32 v[82:83], v[226:227], s[58:59], v[80:81] op_sel_hi:[1,1,0]
	v_pk_fma_f32 v[80:81], v[134:135], s[60:61], v[80:81] op_sel_hi:[1,1,0]
	s_waitcnt lgkmcnt(1)
	v_mfma_f32_32x32x16_bf16 v[96:111], v[230:233], v[112:115], v[96:111]
	s_waitcnt lgkmcnt(0)
	v_mfma_f32_32x32x16_bf16 v[80:95], v[234:237], v[112:115], v[80:95]
	ds_read_b128 v[230:233], v163 offset:49152
	ds_read_b128 v[234:237], v164 offset:49152
	s_waitcnt lgkmcnt(1)
	v_mfma_f32_32x32x16_bf16 v[96:111], v[230:233], v[116:119], v[96:111]
	s_waitcnt lgkmcnt(0)
	v_mfma_f32_32x32x16_bf16 v[80:95], v[234:237], v[116:119], v[80:95]
	ds_read_b128 v[230:233], v165 offset:49152
	ds_read_b128 v[234:237], v166 offset:49152
	s_waitcnt lgkmcnt(1)
	v_mfma_f32_32x32x16_bf16 v[96:111], v[230:233], v[124:127], v[96:111]
	s_waitcnt lgkmcnt(0)
	v_mfma_f32_32x32x16_bf16 v[80:95], v[234:237], v[124:127], v[80:95]
	ds_read_b128 v[230:233], v168 offset:49152
	ds_read_b128 v[234:237], v169 offset:49152
	s_waitcnt lgkmcnt(1)
	v_mfma_f32_32x32x16_bf16 v[96:111], v[230:233], v[120:123], v[96:111]
	s_waitcnt lgkmcnt(0)
	v_mfma_f32_32x32x16_bf16 v[80:95], v[234:237], v[120:123], v[80:95]
	s_cbranch_scc1 .LvB_471
	s_sub_i32 s6, s6, s14
	v_or_b32_e32 v228, s6, v155
	v_cmp_lt_i32_e32 vcc, v228, v153
	v_or_b32_e32 v229, 2, v228
	s_nop 4
	v_cndmask_b32_e32 v97, v145, v97, vcc
	v_cmp_le_i32_e32 vcc, v228, v153
	s_nop 1
	v_cndmask_b32_e32 v96, v145, v96, vcc
	v_cmp_lt_i32_e32 vcc, v228, v160
	s_nop 1
	v_cndmask_b32_e32 v81, v145, v81, vcc
	v_cmp_le_i32_e32 vcc, v228, v160
	s_nop 1
	v_cndmask_b32_e32 v80, v145, v80, vcc
	v_cmp_le_i32_e32 vcc, v229, v153
	s_nop 1
	v_cndmask_b32_e32 v98, v145, v98, vcc
	v_cmp_le_i32_e32 vcc, v229, v160
	v_or_b32_e32 v229, 3, v228
	s_nop 0
	v_cndmask_b32_e32 v82, v145, v82, vcc
	v_cmp_le_i32_e32 vcc, v229, v153
	s_nop 1
	v_cndmask_b32_e32 v99, v145, v99, vcc
	v_cmp_le_i32_e32 vcc, v229, v160
	v_or_b32_e32 v229, 8, v228
	s_nop 0
	v_cndmask_b32_e32 v83, v145, v83, vcc
	v_cmp_le_i32_e32 vcc, v229, v153
	s_nop 1
	v_cndmask_b32_e32 v100, v145, v100, vcc
	v_cmp_le_i32_e32 vcc, v229, v160
	v_or_b32_e32 v229, 9, v228
	s_nop 0
	v_cndmask_b32_e32 v84, v145, v84, vcc
	v_cmp_le_i32_e32 vcc, v229, v153
	s_nop 1
	v_cndmask_b32_e32 v101, v145, v101, vcc
	v_cmp_le_i32_e32 vcc, v229, v160
	v_or_b32_e32 v229, 10, v228
	s_nop 0
	v_cndmask_b32_e32 v85, v145, v85, vcc
	v_cmp_le_i32_e32 vcc, v229, v153
	s_nop 1
	v_cndmask_b32_e32 v102, v145, v102, vcc
	v_cmp_le_i32_e32 vcc, v229, v160
	v_or_b32_e32 v229, 11, v228
	s_nop 0
	v_cndmask_b32_e32 v86, v145, v86, vcc
	v_cmp_le_i32_e32 vcc, v229, v153
	s_nop 1
	v_cndmask_b32_e32 v103, v145, v103, vcc
	v_cmp_le_i32_e32 vcc, v229, v160
	v_or_b32_e32 v229, 16, v228
	s_nop 0
	v_cndmask_b32_e32 v87, v145, v87, vcc
	v_cmp_le_i32_e32 vcc, v229, v153
	s_nop 1
	v_cndmask_b32_e32 v104, v145, v104, vcc
	v_cmp_le_i32_e32 vcc, v229, v160
	v_or_b32_e32 v229, 17, v228
	s_nop 0
	v_cndmask_b32_e32 v88, v145, v88, vcc
	v_cmp_le_i32_e32 vcc, v229, v153
	s_nop 1
	v_cndmask_b32_e32 v105, v145, v105, vcc
	v_cmp_le_i32_e32 vcc, v229, v160
	v_or_b32_e32 v229, 18, v228
	s_nop 0
	v_cndmask_b32_e32 v89, v145, v89, vcc
	v_cmp_le_i32_e32 vcc, v229, v153
	s_nop 1
	v_cndmask_b32_e32 v106, v145, v106, vcc
	v_cmp_le_i32_e32 vcc, v229, v160
	v_or_b32_e32 v229, 19, v228
	s_nop 0
	v_cndmask_b32_e32 v90, v145, v90, vcc
	v_cmp_le_i32_e32 vcc, v229, v153
	s_nop 1
	v_cndmask_b32_e32 v107, v145, v107, vcc
	v_cmp_le_i32_e32 vcc, v229, v160
	v_or_b32_e32 v229, 24, v228
	s_nop 0
	v_cndmask_b32_e32 v91, v145, v91, vcc
	v_cmp_le_i32_e32 vcc, v229, v153
	s_nop 1
	v_cndmask_b32_e32 v108, v145, v108, vcc
	v_cmp_le_i32_e32 vcc, v229, v160
	v_or_b32_e32 v229, 25, v228
	s_nop 0
	v_cndmask_b32_e32 v92, v145, v92, vcc
	v_cmp_le_i32_e32 vcc, v229, v153
	s_nop 1
	v_cndmask_b32_e32 v109, v145, v109, vcc
	v_cmp_le_i32_e32 vcc, v229, v160
	v_or_b32_e32 v229, 26, v228
	v_or_b32_e32 v228, 27, v228
	v_cndmask_b32_e32 v93, v145, v93, vcc
	v_cmp_le_i32_e32 vcc, v229, v153
	s_nop 1
	v_cndmask_b32_e32 v110, v145, v110, vcc
	v_cmp_le_i32_e32 vcc, v229, v160
	s_nop 1
	v_cndmask_b32_e32 v94, v145, v94, vcc
	v_cmp_le_i32_e32 vcc, v228, v153
	s_nop 1
	v_cndmask_b32_e32 v111, v145, v111, vcc
	v_cmp_le_i32_e32 vcc, v228, v160
	s_nop 1
	v_cndmask_b32_e32 v95, v145, v95, vcc
.LvB_471:
	s_nop 15
	v_max_f32_e32 v131, v97, v97
	v_max_f32_e32 v183, v96, v96
	v_max_f32_e32 v131, v183, v131
	v_max3_f32 v131, v131, v98, v99
	v_max3_f32 v131, v131, v100, v101
	v_max3_f32 v131, v131, v102, v103
	v_max3_f32 v131, v131, v104, v105
	v_max3_f32 v131, v131, v106, v107
	v_max3_f32 v131, v131, v108, v109
	v_max3_f32 v131, v131, v110, v111
	v_max3_f32 v131, v131, v80, v81
	v_max3_f32 v131, v131, v82, v83
	v_max3_f32 v131, v131, v84, v85
	v_max3_f32 v131, v131, v86, v87
	v_max3_f32 v131, v131, v88, v89
	v_max3_f32 v131, v131, v90, v91
	v_max3_f32 v131, v131, v92, v93
	v_max3_f32 v131, v131, v94, v95
	v_mov_b32_e32 v183, v131
	s_nop 1
	v_permlane32_swap_b32_e32 v131, v183
	v_max_f32_e32 v183, v183, v183
	v_max_f32_e32 v131, v131, v131
	v_max_f32_e32 v131, v131, v183
	v_sub_f32_e32 v183, v131, v177
	v_cmp_ge_f32_e32 vcc, s16, v183
	v_max_f32_e32 v183, v177, v177
	v_max_f32_e32 v131, v183, v131
	v_sub_f32_e32 v183, v177, v131
	v_exp_f32_e32 v183, v183
	s_cmp_eq_u64 vcc, exec
	s_cselect_b64 s[6:7], -1, 0
	s_barrier
	s_waitcnt vmcnt(0)
	v_cndmask_b32_e64 v199, v183, 1.0, s[6:7]
	v_cmp_gt_f32_e32 vcc, 1.0, v199
	s_waitcnt vmcnt(3)
	ds_write_b128 v174, v[64:67]
	s_waitcnt vmcnt(2)
	ds_write_b128 v175, v[68:71]
	s_waitcnt vmcnt(1)
	ds_write_b128 v171, v[72:75] offset:32768
	s_waitcnt vmcnt(0)
	ds_write_b128 v172, v[76:79] offset:32768
	s_cbranch_vccz .LvB_475
	s_and_saveexec_b64 s[68:69], s[4:5]
	ds_write_b32 v179, v199 offset:128
	s_or_b64 exec, exec, s[68:69]
	s_waitcnt lgkmcnt(0)
	ds_read_b128 v[64:67], v173 offset:224
	ds_read_b128 v[68:71], v173 offset:192
	ds_read_b128 v[72:75], v173 offset:160
	ds_read_b128 v[76:79], v173 offset:128
	s_waitcnt lgkmcnt(3)
	v_pk_mul_f32 v[62:63], v[62:63], v[66:67]
	s_waitcnt lgkmcnt(2)
	v_pk_mul_f32 v[58:59], v[58:59], v[70:71]
	s_waitcnt lgkmcnt(1)
	v_pk_mul_f32 v[54:55], v[54:55], v[74:75]
	s_waitcnt lgkmcnt(0)
	v_pk_mul_f32 v[50:51], v[50:51], v[78:79]
	v_pk_mul_f32 v[60:61], v[60:61], v[64:65]
	v_pk_mul_f32 v[56:57], v[56:57], v[68:69]
	v_pk_mul_f32 v[52:53], v[52:53], v[72:73]
	v_pk_mul_f32 v[48:49], v[48:49], v[76:77]
	v_pk_mul_f32 v[46:47], v[46:47], v[66:67]
	v_pk_mul_f32 v[42:43], v[42:43], v[70:71]
	v_pk_mul_f32 v[38:39], v[38:39], v[74:75]
	v_pk_mul_f32 v[34:35], v[34:35], v[78:79]
	v_pk_mul_f32 v[44:45], v[44:45], v[64:65]
	v_pk_mul_f32 v[40:41], v[40:41], v[68:69]
	v_pk_mul_f32 v[36:37], v[36:37], v[72:73]
	v_pk_mul_f32 v[32:33], v[32:33], v[76:77]
	v_pk_mul_f32 v[30:31], v[30:31], v[66:67]
	v_pk_mul_f32 v[26:27], v[26:27], v[70:71]
	v_pk_mul_f32 v[22:23], v[22:23], v[74:75]
	v_pk_mul_f32 v[18:19], v[18:19], v[78:79]
	v_pk_mul_f32 v[28:29], v[28:29], v[64:65]
	v_pk_mul_f32 v[24:25], v[24:25], v[68:69]
	v_pk_mul_f32 v[20:21], v[20:21], v[72:73]
	v_pk_mul_f32 v[16:17], v[16:17], v[76:77]
	v_pk_mul_f32 v[14:15], v[14:15], v[66:67]
	v_pk_mul_f32 v[10:11], v[10:11], v[70:71]
	v_pk_mul_f32 v[6:7], v[6:7], v[74:75]
	v_pk_mul_f32 v[2:3], v[2:3], v[78:79]
	v_pk_mul_f32 v[12:13], v[12:13], v[64:65]
	v_pk_mul_f32 v[8:9], v[8:9], v[68:69]
	v_pk_mul_f32 v[4:5], v[4:5], v[72:73]
	v_pk_mul_f32 v[0:1], v[0:1], v[76:77]
.LvB_475:
	v_cndmask_b32_e64 v177, v131, v177, s[6:7]
	v_sub_f32_e32 v64, v96, v177
	v_sub_f32_e32 v65, v97, v177
	v_sub_f32_e32 v66, v98, v177
	v_sub_f32_e32 v67, v99, v177
	v_sub_f32_e32 v68, v100, v177
	v_sub_f32_e32 v69, v101, v177
	v_sub_f32_e32 v70, v102, v177
	v_sub_f32_e32 v71, v103, v177
	v_sub_f32_e32 v72, v104, v177
	v_sub_f32_e32 v73, v105, v177
	v_sub_f32_e32 v74, v106, v177
	v_sub_f32_e32 v75, v107, v177
	v_sub_f32_e32 v76, v108, v177
	v_sub_f32_e32 v77, v109, v177
	v_sub_f32_e32 v78, v110, v177
	v_sub_f32_e32 v79, v111, v177
	v_exp_f32_e32 v196, v64
	v_exp_f32_e32 v198, v65
	v_exp_f32_e32 v194, v66
	v_exp_f32_e32 v197, v67
	v_exp_f32_e32 v192, v68
	v_exp_f32_e32 v195, v69
	v_exp_f32_e32 v191, v70
	v_exp_f32_e32 v193, v71
	v_exp_f32_e32 v188, v72
	v_exp_f32_e32 v190, v73
	v_exp_f32_e32 v186, v74
	v_exp_f32_e32 v189, v75
	v_exp_f32_e32 v184, v76
	v_exp_f32_e32 v187, v77
	v_exp_f32_e32 v183, v78
	v_exp_f32_e32 v185, v79
	s_waitcnt lgkmcnt(0)
	s_barrier
	v_add_f32_e32 v131, 0, v196
	v_add_f32_e32 v131, v198, v131
	v_add_f32_e32 v131, v194, v131
	v_add_f32_e32 v131, v197, v131
	v_add_f32_e32 v131, v192, v131
	v_add_f32_e32 v131, v195, v131
	v_add_f32_e32 v131, v191, v131
	v_add_f32_e32 v131, v193, v131
	v_add_f32_e32 v131, v188, v131
	v_add_f32_e32 v131, v190, v131
	v_add_f32_e32 v131, v186, v131
	v_sub_f32_e32 v80, v80, v177
	v_add_f32_e32 v131, v189, v131
	v_sub_f32_e32 v81, v81, v177
	v_exp_f32_e32 v80, v80
	v_add_f32_e32 v131, v184, v131
	v_sub_f32_e32 v82, v82, v177
	v_exp_f32_e32 v81, v81
	v_add_f32_e32 v131, v187, v131
	v_sub_f32_e32 v83, v83, v177
	v_exp_f32_e32 v82, v82
	v_add_f32_e32 v131, v183, v131
	v_sub_f32_e32 v84, v84, v177
	v_exp_f32_e32 v83, v83
	v_add_f32_e32 v131, v185, v131
	v_sub_f32_e32 v85, v85, v177
	v_exp_f32_e32 v84, v84
	v_add_f32_e32 v131, v80, v131
	v_sub_f32_e32 v86, v86, v177
	v_exp_f32_e32 v85, v85
	v_add_f32_e32 v131, v81, v131
	v_sub_f32_e32 v87, v87, v177
	v_exp_f32_e32 v86, v86
	v_add_f32_e32 v131, v82, v131
	v_sub_f32_e32 v88, v88, v177
	v_exp_f32_e32 v87, v87
	v_add_f32_e32 v131, v83, v131
	v_sub_f32_e32 v89, v89, v177
	v_exp_f32_e32 v88, v88
	v_add_f32_e32 v131, v84, v131
	v_sub_f32_e32 v90, v90, v177
	v_exp_f32_e32 v89, v89
	v_add_f32_e32 v131, v85, v131
	v_sub_f32_e32 v91, v91, v177
	v_exp_f32_e32 v90, v90
	v_add_f32_e32 v131, v86, v131
	v_sub_f32_e32 v92, v92, v177
	v_exp_f32_e32 v91, v91
	v_add_f32_e32 v131, v87, v131
	v_sub_f32_e32 v93, v93, v177
	v_exp_f32_e32 v92, v92
	v_add_f32_e32 v131, v88, v131
	v_sub_f32_e32 v94, v94, v177
	v_exp_f32_e32 v93, v93
	v_add_f32_e32 v131, v89, v131
	v_sub_f32_e32 v95, v95, v177
	v_exp_f32_e32 v94, v94
	v_add_f32_e32 v131, v90, v131
	v_exp_f32_e32 v95, v95
	v_add_f32_e32 v131, v91, v131
	v_add_f32_e32 v131, v92, v131
	v_add_f32_e32 v131, v93, v131
	v_add_f32_e32 v131, v94, v131
	v_add_f32_e32 v131, v95, v131
	v_mov_b32_e32 v200, v131
	s_nop 1
	v_permlane32_swap_b32_e32 v131, v200
	v_cvt_pk_bf16_f32 v202, v196, v198
	v_cvt_pk_bf16_f32 v203, v194, v197
	v_cvt_pk_bf16_f32 v204, v192, v195
	v_cvt_pk_bf16_f32 v205, v191, v193
	v_cvt_pk_bf16_f32 v188, v188, v190
	v_cvt_pk_bf16_f32 v189, v186, v189
	v_cvt_pk_bf16_f32 v190, v184, v187
	v_cvt_pk_bf16_f32 v191, v183, v185
	v_cvt_pk_bf16_f32 v184, v80, v81
	v_cvt_pk_bf16_f32 v185, v82, v83
	v_cvt_pk_bf16_f32 v186, v84, v85
	v_cvt_pk_bf16_f32 v187, v86, v87
	v_cvt_pk_bf16_f32 v192, v88, v89
	v_cvt_pk_bf16_f32 v193, v90, v91
	v_cvt_pk_bf16_f32 v194, v92, v93
	v_cvt_pk_bf16_f32 v195, v94, v95
	s_nop 0
	v_permlane32_swap_b32_e32 v202, v204
	v_permlane32_swap_b32_e32 v203, v205
	v_permlane32_swap_b32_e32 v188, v190
	v_permlane32_swap_b32_e32 v189, v191
	v_permlane32_swap_b32_e32 v184, v186
	v_permlane32_swap_b32_e32 v185, v187
	v_permlane32_swap_b32_e32 v192, v194
	v_permlane32_swap_b32_e32 v193, v195
	s_and_b64 s[6:7], s[64:65], exec
	s_cselect_b32 s6, s29, s30
	s_lshl_b32 s6, s6, 6
	v_add_u32_e32 v80, s6, v158
	v_add_u32_e32 v82, s6, v170
	v_ashrrev_i32_e32 v81, 31, v80
	v_ashrrev_i32_e32 v83, 31, v82
	v_lshlrev_b64 v[88:89], 10, v[80:81]
	v_lshlrev_b64 v[90:91], 10, v[82:83]
	v_lshl_add_u64 v[80:81], v[132:133], 0, v[88:89]
	v_lshl_add_u64 v[84:85], v[132:133], 0, v[90:91]
	v_lshl_add_u64 v[88:89], v[138:139], 0, v[88:89]
	v_lshl_add_u64 v[92:93], v[138:139], 0, v[90:91]
	global_load_dwordx4 v[80:83], v[80:81], off
	s_nop 0
	global_load_dwordx4 v[84:87], v[84:85], off
	s_nop 0
	global_load_dwordx4 v[88:91], v[88:89], off
	s_nop 0
	global_load_dwordx4 v[92:95], v[92:93], off
	ds_read_b64_tr_b16 v[206:207], v180 offset:0
	ds_read_b64_tr_b16 v[208:209], v180 offset:0x800
	ds_read_b64_tr_b16 v[210:211], v180 offset:0x1000
	ds_read_b64_tr_b16 v[212:213], v180 offset:0x1800
	ds_read_b64_tr_b16 v[214:215], v180 offset:0x2000
	ds_read_b64_tr_b16 v[216:217], v180 offset:0x2800
	ds_read_b64_tr_b16 v[218:219], v180 offset:0x3000
	ds_read_b64_tr_b16 v[220:221], v180 offset:0x3800
	s_waitcnt lgkmcnt(0)
	s_nop 0
	v_mfma_f32_32x32x16_bf16 v[48:63], v[202:205], v[206:209], v[48:63]
	ds_read_b64_tr_b16 v[206:207], v180 offset:0x200
	ds_read_b64_tr_b16 v[208:209], v180 offset:0xa00
	v_mfma_f32_32x32x16_bf16 v[48:63], v[188:191], v[210:213], v[48:63]
	ds_read_b64_tr_b16 v[210:211], v180 offset:0x1200
	ds_read_b64_tr_b16 v[212:213], v180 offset:0x1a00
	v_mfma_f32_32x32x16_bf16 v[48:63], v[184:187], v[214:217], v[48:63]
	ds_read_b64_tr_b16 v[214:215], v180 offset:0x2200
	ds_read_b64_tr_b16 v[216:217], v180 offset:0x2a00
	ds_read_b64_tr_b16 v[222:223], v180 offset:0x3200
	ds_read_b64_tr_b16 v[224:225], v180 offset:0x3a00
	s_waitcnt lgkmcnt(0)
	v_mfma_f32_32x32x16_bf16 v[48:63], v[192:195], v[218:221], v[48:63]
	v_mfma_f32_32x32x16_bf16 v[32:47], v[202:205], v[206:209], v[32:47]
	ds_read_b64_tr_b16 v[206:207], v180 offset:0x400
	ds_read_b64_tr_b16 v[208:209], v180 offset:0xc00
	v_mfma_f32_32x32x16_bf16 v[32:47], v[188:191], v[210:213], v[32:47]
	ds_read_b64_tr_b16 v[210:211], v180 offset:0x1400
	ds_read_b64_tr_b16 v[212:213], v180 offset:0x1c00
	v_mfma_f32_32x32x16_bf16 v[32:47], v[184:187], v[214:217], v[32:47]
	ds_read_b64_tr_b16 v[214:215], v180 offset:0x2400
	ds_read_b64_tr_b16 v[216:217], v180 offset:0x2c00
	ds_read_b64_tr_b16 v[218:219], v180 offset:0x3400
	ds_read_b64_tr_b16 v[220:221], v180 offset:0x3c00
	s_waitcnt lgkmcnt(0)
	v_mfma_f32_32x32x16_bf16 v[32:47], v[192:195], v[222:225], v[32:47]
	v_mfma_f32_32x32x16_bf16 v[16:31], v[202:205], v[206:209], v[16:31]
	ds_read_b64_tr_b16 v[206:207], v180 offset:0x600
	ds_read_b64_tr_b16 v[208:209], v180 offset:0xe00
	v_mfma_f32_32x32x16_bf16 v[16:31], v[188:191], v[210:213], v[16:31]
	ds_read_b64_tr_b16 v[210:211], v180 offset:0x1600
	ds_read_b64_tr_b16 v[212:213], v180 offset:0x1e00
	v_mfma_f32_32x32x16_bf16 v[16:31], v[184:187], v[214:217], v[16:31]
	ds_read_b64_tr_b16 v[214:215], v180 offset:0x2600
	ds_read_b64_tr_b16 v[216:217], v180 offset:0x2e00
	ds_read_b64_tr_b16 v[222:223], v180 offset:0x3600
	ds_read_b64_tr_b16 v[224:225], v180 offset:0x3e00
	s_waitcnt lgkmcnt(0)
	v_mfma_f32_32x32x16_bf16 v[16:31], v[192:195], v[218:221], v[16:31]
	v_mfma_f32_32x32x16_bf16 v[0:15], v[202:205], v[206:209], v[0:15]
	s_barrier
	s_waitcnt vmcnt(0)
	s_waitcnt vmcnt(3)
	ds_write_b128 v174, v[80:83] offset:16384
	s_waitcnt vmcnt(2)
	ds_write_b128 v175, v[84:87] offset:16384
	s_waitcnt vmcnt(1)
	ds_write_b128 v171, v[88:91] offset:49152
	s_waitcnt vmcnt(0)
	ds_write_b128 v172, v[92:95] offset:49152
	v_mfma_f32_32x32x16_bf16 v[0:15], v[188:191], v[210:213], v[0:15]
	v_mfma_f32_32x32x16_bf16 v[0:15], v[184:187], v[214:217], v[0:15]
	v_mfma_f32_32x32x16_bf16 v[0:15], v[192:195], v[222:225], v[0:15]
	ds_read_b128 v[96:99], v167 offset:32768
	ds_read_b128 v[230:233], v162 offset:32768
	v_add_u32_e32 v64, s24, v178
	v_cvt_f32_i32_e32 v64, v64
	v_mov_b32_e32 v226, v130
	v_mov_b32_e32 v227, v130
	s_cmp_lt_i32 s25, s28
	v_mul_f32_e32 v204, v130, v64
	v_pk_add_f32 v[64:65], v[128:129], v[204:205] op_sel_hi:[1,0]
	v_pk_fma_f32 v[66:67], v[136:137], s[10:11], v[204:205] op_sel_hi:[1,1,0]
	v_pk_fma_f32 v[68:69], v[136:137], s[16:17], v[204:205] op_sel_hi:[1,1,0]
	v_pk_fma_f32 v[70:71], v[136:137], s[18:19], v[204:205] op_sel_hi:[1,1,0]
	v_pk_fma_f32 v[72:73], v[136:137], s[22:23], v[204:205] op_sel_hi:[1,1,0]
	v_pk_fma_f32 v[74:75], v[136:137], s[40:41], v[204:205] op_sel_hi:[1,1,0]
	v_pk_fma_f32 v[76:77], v[136:137], s[42:43], v[204:205] op_sel_hi:[1,1,0]
	v_pk_fma_f32 v[78:79], v[136:137], s[44:45], v[204:205] op_sel_hi:[1,1,0]
	v_pk_fma_f32 v[110:111], v[226:227], s[46:47], v[204:205] op_sel_hi:[1,1,0]
	v_pk_fma_f32 v[108:109], v[226:227], s[48:49], v[204:205] op_sel_hi:[1,1,0]
	s_waitcnt lgkmcnt(1)
	v_mfma_f32_32x32x16_bf16 v[64:79], v[96:99], v[112:115], v[64:79]
	v_fma_f32 v106, v130, s50, v204
	v_fma_f32 v107, v227, s51, v204
	v_fma_f32 v104, v130, s52, v204
	v_fma_f32 v105, v227, s53, v204
	v_fma_f32 v102, v130, s54, v204
	v_fma_f32 v103, v227, s55, v204
	v_pk_fma_f32 v[100:101], v[226:227], s[56:57], v[204:205] op_sel_hi:[1,1,0]
	v_pk_fma_f32 v[98:99], v[226:227], s[58:59], v[204:205] op_sel_hi:[1,1,0]
	v_pk_fma_f32 v[96:97], v[134:135], s[60:61], v[204:205] op_sel_hi:[1,1,0]
	s_waitcnt lgkmcnt(0)
	s_nop 0
	v_mfma_f32_32x32x16_bf16 v[96:111], v[230:233], v[112:115], v[96:111]
	ds_read_b128 v[230:233], v163 offset:32768
	ds_read_b128 v[204:207], v164 offset:32768
	s_waitcnt lgkmcnt(1)
	v_mfma_f32_32x32x16_bf16 v[64:79], v[230:233], v[116:119], v[64:79]
	s_waitcnt lgkmcnt(0)
	v_mfma_f32_32x32x16_bf16 v[96:111], v[204:207], v[116:119], v[96:111]
	ds_read_b128 v[230:233], v165 offset:32768
	ds_read_b128 v[204:207], v166 offset:32768
	s_waitcnt lgkmcnt(1)
	v_mfma_f32_32x32x16_bf16 v[64:79], v[230:233], v[124:127], v[64:79]
	s_waitcnt lgkmcnt(0)
	v_mfma_f32_32x32x16_bf16 v[96:111], v[204:207], v[124:127], v[96:111]
	ds_read_b128 v[230:233], v168 offset:32768
	ds_read_b128 v[204:207], v169 offset:32768
	s_waitcnt lgkmcnt(1)
	v_mfma_f32_32x32x16_bf16 v[64:79], v[230:233], v[120:123], v[64:79]
	s_waitcnt lgkmcnt(0)
	v_mfma_f32_32x32x16_bf16 v[96:111], v[204:207], v[120:123], v[96:111]
	s_cbranch_scc1 .LvB_477
	s_sub_i32 s6, s24, s14
	v_or_b32_e32 v228, s6, v155
	v_cmp_lt_i32_e32 vcc, v228, v153
	v_or_b32_e32 v238, 2, v228
	s_nop 4
	v_cndmask_b32_e32 v65, v145, v65, vcc
	v_cmp_le_i32_e32 vcc, v228, v153
	s_nop 1
	v_cndmask_b32_e32 v64, v145, v64, vcc
	v_cmp_lt_i32_e32 vcc, v228, v160
	s_nop 1
	v_cndmask_b32_e32 v97, v145, v97, vcc
	v_cmp_le_i32_e32 vcc, v228, v160
	s_nop 1
	v_cndmask_b32_e32 v96, v145, v96, vcc
	v_cmp_le_i32_e32 vcc, v238, v153
	s_nop 1
	v_cndmask_b32_e32 v66, v145, v66, vcc
	v_cmp_le_i32_e32 vcc, v238, v160
	v_or_b32_e32 v238, 3, v228
	s_nop 0
	v_cndmask_b32_e32 v98, v145, v98, vcc
	v_cmp_le_i32_e32 vcc, v238, v153
	s_nop 1
	v_cndmask_b32_e32 v67, v145, v67, vcc
	v_cmp_le_i32_e32 vcc, v238, v160
	v_or_b32_e32 v238, 8, v228
	s_nop 0
	v_cndmask_b32_e32 v99, v145, v99, vcc
	v_cmp_le_i32_e32 vcc, v238, v153
	s_nop 1
	v_cndmask_b32_e32 v68, v145, v68, vcc
	v_cmp_le_i32_e32 vcc, v238, v160
	v_or_b32_e32 v238, 9, v228
	s_nop 0
	v_cndmask_b32_e32 v100, v145, v100, vcc
	v_cmp_le_i32_e32 vcc, v238, v153
	s_nop 1
	v_cndmask_b32_e32 v69, v145, v69, vcc
	v_cmp_le_i32_e32 vcc, v238, v160
	v_or_b32_e32 v238, 10, v228
	s_nop 0
	v_cndmask_b32_e32 v101, v145, v101, vcc
	v_cmp_le_i32_e32 vcc, v238, v153
	s_nop 1
	v_cndmask_b32_e32 v70, v145, v70, vcc
	v_cmp_le_i32_e32 vcc, v238, v160
	v_or_b32_e32 v238, 11, v228
	s_nop 0
	v_cndmask_b32_e32 v102, v145, v102, vcc
	v_cmp_le_i32_e32 vcc, v238, v153
	s_nop 1
	v_cndmask_b32_e32 v71, v145, v71, vcc
	v_cmp_le_i32_e32 vcc, v238, v160
	v_or_b32_e32 v238, 16, v228
	s_nop 0
	v_cndmask_b32_e32 v103, v145, v103, vcc
	v_cmp_le_i32_e32 vcc, v238, v153
	s_nop 1
	v_cndmask_b32_e32 v72, v145, v72, vcc
	v_cmp_le_i32_e32 vcc, v238, v160
	v_or_b32_e32 v238, 17, v228
	s_nop 0
	v_cndmask_b32_e32 v104, v145, v104, vcc
	v_cmp_le_i32_e32 vcc, v238, v153
	s_nop 1
	v_cndmask_b32_e32 v73, v145, v73, vcc
	v_cmp_le_i32_e32 vcc, v238, v160
	v_or_b32_e32 v238, 18, v228
	s_nop 0
	v_cndmask_b32_e32 v105, v145, v105, vcc
	v_cmp_le_i32_e32 vcc, v238, v153
	s_nop 1
	v_cndmask_b32_e32 v74, v145, v74, vcc
	v_cmp_le_i32_e32 vcc, v238, v160
	v_or_b32_e32 v238, 19, v228
	s_nop 0
	v_cndmask_b32_e32 v106, v145, v106, vcc
	v_cmp_le_i32_e32 vcc, v238, v153
	s_nop 1
	v_cndmask_b32_e32 v75, v145, v75, vcc
	v_cmp_le_i32_e32 vcc, v238, v160
	v_or_b32_e32 v238, 24, v228
	s_nop 0
	v_cndmask_b32_e32 v107, v145, v107, vcc
	v_cmp_le_i32_e32 vcc, v238, v153
	s_nop 1
	v_cndmask_b32_e32 v76, v145, v76, vcc
	v_cmp_le_i32_e32 vcc, v238, v160
	v_or_b32_e32 v238, 25, v228
	s_nop 0
	v_cndmask_b32_e32 v108, v145, v108, vcc
	v_cmp_le_i32_e32 vcc, v238, v153
	s_nop 1
	v_cndmask_b32_e32 v77, v145, v77, vcc
	v_cmp_le_i32_e32 vcc, v238, v160
	v_or_b32_e32 v238, 26, v228
	v_or_b32_e32 v228, 27, v228
	v_cndmask_b32_e32 v109, v145, v109, vcc
	v_cmp_le_i32_e32 vcc, v238, v153
	s_nop 1
	v_cndmask_b32_e32 v78, v145, v78, vcc
	v_cmp_le_i32_e32 vcc, v238, v160
	s_nop 1
	v_cndmask_b32_e32 v110, v145, v110, vcc
	v_cmp_le_i32_e32 vcc, v228, v153
	s_nop 1
	v_cndmask_b32_e32 v79, v145, v79, vcc
	v_cmp_le_i32_e32 vcc, v228, v160
	s_nop 1
	v_cndmask_b32_e32 v111, v145, v111, vcc
.LvB_477:
	s_nop 15
	v_max_f32_e32 v183, v65, v65
	v_max_f32_e32 v184, v64, v64
	v_max_f32_e32 v183, v184, v183
	v_max3_f32 v183, v183, v66, v67
	v_max3_f32 v183, v183, v68, v69
	v_max3_f32 v183, v183, v70, v71
	v_max3_f32 v183, v183, v72, v73
	v_max3_f32 v183, v183, v74, v75
	v_max3_f32 v183, v183, v76, v77
	v_max3_f32 v183, v183, v78, v79
	v_max3_f32 v183, v183, v96, v97
	v_max3_f32 v183, v183, v98, v99
	v_max3_f32 v183, v183, v100, v101
	v_max3_f32 v183, v183, v102, v103
	v_max3_f32 v183, v183, v104, v105
	v_max3_f32 v183, v183, v106, v107
	v_max3_f32 v183, v183, v108, v109
	v_max3_f32 v183, v183, v110, v111
	v_mov_b32_e32 v184, v183
	s_nop 1
	v_permlane32_swap_b32_e32 v183, v184
	v_max_f32_e32 v184, v184, v184
	v_max_f32_e32 v183, v183, v183
	v_max_f32_e32 v183, v183, v184
	v_sub_f32_e32 v184, v183, v177
	v_cmp_ge_f32_e32 vcc, s16, v184
	v_max_f32_e32 v184, v177, v177
	v_max_f32_e32 v183, v184, v183
	v_sub_f32_e32 v184, v177, v183
	v_exp_f32_e32 v184, v184
	s_cmp_eq_u64 vcc, exec
	s_cselect_b64 s[6:7], -1, 0
	v_cndmask_b32_e64 v201, v184, 1.0, s[6:7]
	v_cmp_gt_f32_e32 vcc, 1.0, v201
	s_cbranch_vccz .LvB_481
	s_and_saveexec_b64 s[68:69], s[4:5]
	ds_write_b32 v179, v201 offset:128
	s_or_b64 exec, exec, s[68:69]
	s_waitcnt lgkmcnt(0)
	ds_read_b128 v[80:83], v173 offset:224
	ds_read_b128 v[84:87], v173 offset:192
	ds_read_b128 v[88:91], v173 offset:160
	ds_read_b128 v[92:95], v173 offset:128
	s_waitcnt lgkmcnt(3)
	v_pk_mul_f32 v[62:63], v[62:63], v[82:83]
	s_waitcnt lgkmcnt(2)
	v_pk_mul_f32 v[58:59], v[58:59], v[86:87]
	s_waitcnt lgkmcnt(1)
	v_pk_mul_f32 v[54:55], v[54:55], v[90:91]
	s_waitcnt lgkmcnt(0)
	v_pk_mul_f32 v[50:51], v[50:51], v[94:95]
	v_pk_mul_f32 v[60:61], v[60:61], v[80:81]
	v_pk_mul_f32 v[56:57], v[56:57], v[84:85]
	v_pk_mul_f32 v[52:53], v[52:53], v[88:89]
	v_pk_mul_f32 v[48:49], v[48:49], v[92:93]
	v_pk_mul_f32 v[46:47], v[46:47], v[82:83]
	v_pk_mul_f32 v[42:43], v[42:43], v[86:87]
	v_pk_mul_f32 v[38:39], v[38:39], v[90:91]
	v_pk_mul_f32 v[34:35], v[34:35], v[94:95]
	v_pk_mul_f32 v[44:45], v[44:45], v[80:81]
	v_pk_mul_f32 v[40:41], v[40:41], v[84:85]
	v_pk_mul_f32 v[36:37], v[36:37], v[88:89]
	v_pk_mul_f32 v[32:33], v[32:33], v[92:93]
	v_pk_mul_f32 v[30:31], v[30:31], v[82:83]
	v_pk_mul_f32 v[26:27], v[26:27], v[86:87]
	v_pk_mul_f32 v[22:23], v[22:23], v[90:91]
	v_pk_mul_f32 v[18:19], v[18:19], v[94:95]
	v_pk_mul_f32 v[28:29], v[28:29], v[80:81]
	v_pk_mul_f32 v[24:25], v[24:25], v[84:85]
	v_pk_mul_f32 v[20:21], v[20:21], v[88:89]
	v_pk_mul_f32 v[16:17], v[16:17], v[92:93]
	v_pk_mul_f32 v[14:15], v[14:15], v[82:83]
	v_pk_mul_f32 v[10:11], v[10:11], v[86:87]
	v_pk_mul_f32 v[6:7], v[6:7], v[90:91]
	v_pk_mul_f32 v[2:3], v[2:3], v[94:95]
	v_pk_mul_f32 v[12:13], v[12:13], v[80:81]
	v_pk_mul_f32 v[8:9], v[8:9], v[84:85]
	v_pk_mul_f32 v[4:5], v[4:5], v[88:89]
	v_pk_mul_f32 v[0:1], v[0:1], v[92:93]
